# FFN-up epilogue rewritten: 8 interleaved sigmoid chains per row group, v_permlane16_swap pairs and one 16-byte store per lane instead of two 8-byte stores
# speedup vs baseline: 1.0078x; 1.0078x over previous
; #define PG8_STAGE(bufoff, gbase, voff) do { _Pragma("unroll") for (int _i = 0; _i < 2; ++_i) \
;     __builtin_amdgcn_global_load_lds((const unsigned*)((const char*)(gbase) + (voff)[_i]), (PG8_LAS unsigned*)(lds + (bufoff) + ldsw + _i * 8192), 16, 0, 0); } while (0)
; #define PG8_LDA(dst, b, h) do { _Pragma("unroll") for (int m = 0; m < 4; ++m) _Pragma("unroll") for (int k = 0; k < 2; ++k) dst[m][k] = *(const PG8_LAS bf16x8*)(lds + PG8_SA(b, h) + aoff + m * 2048 + k * 1024); } while (0)
; #define PG8_LDB(dst, b, h) do { _Pragma("unroll") for (int n = 0; n < 2; ++n) _Pragma("unroll") for (int k = 0; k < 2; ++k) dst[n][k] = *(const PG8_LAS bf16x8*)(lds + PG8_SB(b, h) + boff + n * 2048 + k * 1024); } while (0)
; #define PG8_MMA(ai, bj, At, Bt) do { __builtin_amdgcn_s_setprio(1); _Pragma("unroll") for (int m = 0; m < 4; ++m) _Pragma("unroll") for (int n = 0; n < 2; ++n) _Pragma("unroll") for (int k = 0; k < 2; ++k) \
;     acc[ai][bj][m][n] = __builtin_amdgcn_mfma_f32_16x16x32_bf16(Bt[n][k], At[m][k], acc[ai][bj][m][n], 0, 0, 0); __builtin_amdgcn_s_setprio(0); } while (0)
; #define PG8_WAIT_V(n) asm volatile("s_waitcnt vmcnt(" #n ")" ::: "memory")
; #define PG8_WAIT_L(n) asm volatile("s_waitcnt lgkmcnt(" #n ")" ::: "memory")
; #define PG8_BAR __builtin_amdgcn_s_barrier()
; #define PG8_SCHED __builtin_amdgcn_sched_barrier(0)
; template <class Epi, class Sched>
; __device__ __forceinline__ void gemm_phase(PG8_LAS unsigned char* lds, const int lda, const int ldb, const Sched& S, const Epi& E) {
;     ...
;       PG8_LDB(B0, 0, 0); PG8_SCHED; PG8_LDA(At, 0, 0); PG8_STAGE(PG8_SA(1, 1), a1 + hstepA, voffA);
;       PG8_WAIT_L(8); PG8_BAR; PG8_WAIT_L(0); PG8_MMA(0, 0, At, B0); PG8_BAR; PG8_SCHED;
;       PG8_LDB(B1, 0, 1); PG8_STAGE(PG8_SB(0, 0), b2, voffB);
;       PG8_BAR; PG8_WAIT_L(0); PG8_MMA(0, 1, At, B1); PG8_BAR;
;       PG8_LDA(At, 0, 1); PG8_STAGE(PG8_SA(0, 0), a2, voffA);
;       PG8_BAR; PG8_WAIT_L(0); PG8_MMA(1, 0, At, B0); PG8_BAR; PG8_SCHED;
;       PG8_STAGE(PG8_SB(0, 1), b2 + hstepB, voffB);
;       PG8_WAIT_V(6); PG8_BAR; PG8_MMA(1, 1, At, B1); PG8_BAR;
.LBB0_1604:
	s_add_u32 s20, s18, 0xfffc0080
	s_addc_u32 s21, s19, -1
	s_add_i32 s33, 0, 0x10000
	v_add_u32_e32 v154, s33, v131
	ds_read_b128 v[142:145], v154
	ds_read_b128 v[146:149], v154 offset:1024
	ds_read_b128 v[150:153], v154 offset:2048
	ds_read_b128 v[154:157], v154 offset:3072
	s_cmp_eq_u32 s46, 12
	s_cselect_b32 s23, s11, s21
	s_cselect_b32 s22, s42, s20
	s_cselect_b32 s21, s1, s45
	s_cselect_b32 s20, s43, s44
	v_lshl_add_u64 v[174:175], s[18:19], 0, v[136:137]
	s_add_i32 m0, s17, 0xc000
	ds_read_b128 v[158:161], v141
	ds_read_b128 v[162:165], v141 offset:1024
	ds_read_b128 v[166:169], v141 offset:2048
	ds_read_b128 v[170:173], v141 offset:3072
	ds_read_b128 v[200:203], v141 offset:4096
	ds_read_b128 v[204:207], v141 offset:5120
	ds_read_b128 v[208:211], v141 offset:6144
	ds_read_b128 v[212:215], v141 offset:7168
	global_load_lds_dwordx4 v[174:175], off
	v_lshl_add_u64 v[174:175], s[18:19], 0, v[138:139]
	s_add_i32 m0, s17, 0xe000
	s_nop 0
	global_load_lds_dwordx4 v[174:175], off
	s_waitcnt lgkmcnt(8)
	s_barrier
	s_waitcnt lgkmcnt(0)
	v_mfma_f32_16x16x32_bf16 v[126:129], v[142:145], v[158:161], v[126:129]
	v_mfma_f32_16x16x32_bf16 v[118:121], v[150:153], v[158:161], v[118:121]
	v_mfma_f32_16x16x32_bf16 v[110:113], v[142:145], v[166:169], v[110:113]
	v_mfma_f32_16x16x32_bf16 v[102:105], v[150:153], v[166:169], v[102:105]
	v_mfma_f32_16x16x32_bf16 v[94:97], v[142:145], v[200:203], v[94:97]
	v_mfma_f32_16x16x32_bf16 v[86:89], v[150:153], v[200:203], v[86:89]
	v_mfma_f32_16x16x32_bf16 v[78:81], v[142:145], v[208:211], v[78:81]
	v_mfma_f32_16x16x32_bf16 v[70:73], v[150:153], v[208:211], v[70:73]
	v_mfma_f32_16x16x32_bf16 v[126:129], v[146:149], v[162:165], v[126:129]
	v_mfma_f32_16x16x32_bf16 v[118:121], v[154:157], v[162:165], v[118:121]
	v_mfma_f32_16x16x32_bf16 v[110:113], v[146:149], v[170:173], v[110:113]
	v_mfma_f32_16x16x32_bf16 v[102:105], v[154:157], v[170:173], v[102:105]
	v_mfma_f32_16x16x32_bf16 v[94:97], v[146:149], v[204:207], v[94:97]
	v_mfma_f32_16x16x32_bf16 v[86:89], v[154:157], v[204:207], v[86:89]
	v_mfma_f32_16x16x32_bf16 v[78:81], v[146:149], v[212:215], v[78:81]
	v_mfma_f32_16x16x32_bf16 v[70:73], v[154:157], v[212:215], v[70:73]
	s_barrier
	s_add_i32 s47, 0, 0x14000
	v_add_u32_e32 v174, s47, v131
	s_add_i32 s33, s33, s30
	ds_read_b128 v[216:219], v174
	ds_read_b128 v[220:223], v174 offset:1024
	ds_read_b128 v[224:227], v174 offset:2048
	ds_read_b128 v[228:231], v174 offset:3072
	v_lshl_add_u64 v[174:175], s[20:21], 0, v[134:135]
	s_mov_b32 m0, s33
	v_lshl_add_u64 v[182:183], s[20:21], 0, v[132:133]
	global_load_lds_dwordx4 v[174:175], off
	s_add_i32 m0, s33, 0x2000
	s_nop 0
	global_load_lds_dwordx4 v[182:183], off
	s_barrier
	s_waitcnt lgkmcnt(0)
	v_mfma_f32_16x16x32_bf16 v[122:125], v[216:219], v[158:161], v[122:125]
	v_mfma_f32_16x16x32_bf16 v[114:117], v[224:227], v[158:161], v[114:117]
	v_mfma_f32_16x16x32_bf16 v[106:109], v[216:219], v[166:169], v[106:109]
	v_mfma_f32_16x16x32_bf16 v[98:101], v[224:227], v[166:169], v[98:101]
	v_mfma_f32_16x16x32_bf16 v[90:93], v[216:219], v[200:203], v[90:93]
	v_mfma_f32_16x16x32_bf16 v[82:85], v[224:227], v[200:203], v[82:85]
	v_mfma_f32_16x16x32_bf16 v[74:77], v[216:219], v[208:211], v[74:77]
	v_mfma_f32_16x16x32_bf16 v[66:69], v[224:227], v[208:211], v[66:69]
	v_mfma_f32_16x16x32_bf16 v[122:125], v[220:223], v[162:165], v[122:125]
	v_mfma_f32_16x16x32_bf16 v[114:117], v[228:231], v[162:165], v[114:117]
	v_mfma_f32_16x16x32_bf16 v[106:109], v[220:223], v[170:173], v[106:109]
	v_mfma_f32_16x16x32_bf16 v[98:101], v[228:231], v[170:173], v[98:101]
	v_mfma_f32_16x16x32_bf16 v[90:93], v[220:223], v[204:207], v[90:93]
	v_mfma_f32_16x16x32_bf16 v[82:85], v[228:231], v[204:207], v[82:85]
	v_mfma_f32_16x16x32_bf16 v[74:77], v[220:223], v[212:215], v[74:77]
	v_mfma_f32_16x16x32_bf16 v[66:69], v[228:231], v[212:215], v[66:69]
	s_barrier
	s_mov_b32 m0, s17
	v_lshl_add_u64 v[184:185], s[22:23], 0, v[134:135]
	ds_read_b128 v[158:161], v141 offset:16384
	ds_read_b128 v[162:165], v141 offset:17408
	ds_read_b128 v[166:169], v141 offset:18432
	ds_read_b128 v[170:173], v141 offset:19456
	ds_read_b128 v[200:203], v141 offset:20480
	ds_read_b128 v[204:207], v141 offset:21504
	ds_read_b128 v[208:211], v141 offset:22528
	ds_read_b128 v[212:215], v141 offset:23552
	global_load_lds_dwordx4 v[184:185], off
	v_lshl_add_u64 v[232:233], s[22:23], 0, v[132:133]
	s_mov_b32 m0, s35
	s_nop 0
	global_load_lds_dwordx4 v[232:233], off
	s_barrier
	s_waitcnt lgkmcnt(0)
	v_mfma_f32_16x16x32_bf16 v[62:65], v[142:145], v[158:161], v[62:65]
	v_mfma_f32_16x16x32_bf16 v[54:57], v[150:153], v[158:161], v[54:57]
	v_mfma_f32_16x16x32_bf16 v[46:49], v[142:145], v[166:169], v[46:49]
	v_mfma_f32_16x16x32_bf16 v[38:41], v[150:153], v[166:169], v[38:41]
	v_mfma_f32_16x16x32_bf16 v[30:33], v[142:145], v[200:203], v[30:33]
	v_mfma_f32_16x16x32_bf16 v[22:25], v[150:153], v[200:203], v[22:25]
	v_mfma_f32_16x16x32_bf16 v[14:17], v[142:145], v[208:211], v[14:17]
	v_mfma_f32_16x16x32_bf16 v[6:9], v[150:153], v[208:211], v[6:9]
	v_mfma_f32_16x16x32_bf16 v[62:65], v[146:149], v[162:165], v[62:65]
	v_mfma_f32_16x16x32_bf16 v[54:57], v[154:157], v[162:165], v[54:57]
	v_mfma_f32_16x16x32_bf16 v[46:49], v[146:149], v[170:173], v[46:49]
	v_mfma_f32_16x16x32_bf16 v[38:41], v[154:157], v[170:173], v[38:41]
	v_mfma_f32_16x16x32_bf16 v[30:33], v[146:149], v[204:207], v[30:33]
	v_mfma_f32_16x16x32_bf16 v[22:25], v[154:157], v[204:207], v[22:25]
	v_mfma_f32_16x16x32_bf16 v[14:17], v[146:149], v[212:215], v[14:17]
	v_mfma_f32_16x16x32_bf16 v[6:9], v[154:157], v[212:215], v[6:9]
	s_barrier
; #define PG8_STAGE(bufoff, gbase, voff) do { _Pragma("unroll") for (int _i = 0; _i < 2; ++_i) \
;     __builtin_amdgcn_global_load_lds((const unsigned*)((const char*)(gbase) + (voff)[_i]), (PG8_LAS unsigned*)(lds + (bufoff) + ldsw + _i * 8192), 16, 0, 0); } while (0)
; #define PG8_LDA(dst, b, h) do { _Pragma("unroll") for (int m = 0; m < 4; ++m) _Pragma("unroll") for (int k = 0; k < 2; ++k) dst[m][k] = *(const PG8_LAS bf16x8*)(lds + PG8_SA(b, h) + aoff + m * 2048 + k * 1024); } while (0)
; #define PG8_LDB(dst, b, h) do { _Pragma("unroll") for (int n = 0; n < 2; ++n) _Pragma("unroll") for (int k = 0; k < 2; ++k) dst[n][k] = *(const PG8_LAS bf16x8*)(lds + PG8_SB(b, h) + boff + n * 2048 + k * 1024); } while (0)
; #define PG8_MMA(ai, bj, At, Bt) do { __builtin_amdgcn_s_setprio(1); _Pragma("unroll") for (int m = 0; m < 4; ++m) _Pragma("unroll") for (int n = 0; n < 2; ++n) _Pragma("unroll") for (int k = 0; k < 2; ++k) \
;     acc[ai][bj][m][n] = __builtin_amdgcn_mfma_f32_16x16x32_bf16(Bt[n][k], At[m][k], acc[ai][bj][m][n], 0, 0, 0); __builtin_amdgcn_s_setprio(0); } while (0)
; #define PG8_WAIT_V(n) asm volatile("s_waitcnt vmcnt(" #n ")" ::: "memory")
; #define PG8_WAIT_L(n) asm volatile("s_waitcnt lgkmcnt(" #n ")" ::: "memory")
; #define PG8_BAR __builtin_amdgcn_s_barrier()
; #define PG8_SCHED __builtin_amdgcn_sched_barrier(0)
; template <class Epi, class Sched>
; __device__ __forceinline__ void gemm_phase(PG8_LAS unsigned char* lds, const int lda, const int ldb, const Sched& S, const Epi& E) {
;     ...
;       PG8_STAGE(PG8_SB(0, 1), b2 + hstepB, voffB);
;       PG8_WAIT_V(6); PG8_BAR; PG8_MMA(1, 1, At, B1); PG8_BAR;
;       PG8_LDB(B0, 1, 0); PG8_SCHED; PG8_LDA(At, 1, 0); PG8_STAGE(PG8_SA(0, 1), a2 + hstepA, voffA);
;       PG8_WAIT_L(8); PG8_BAR; PG8_WAIT_L(0); PG8_MMA(0, 0, At, B0); PG8_BAR; PG8_SCHED;
;       PG8_LDB(B1, 1, 1); PG8_STAGE(PG8_SB(1, 0), b3, voffB);
;       PG8_BAR; PG8_WAIT_L(0); PG8_MMA(0, 1, At, B1); PG8_BAR;
;       PG8_LDA(At, 1, 1); PG8_STAGE(PG8_SA(1, 0), a3, voffA);
;       PG8_BAR; PG8_WAIT_L(0); PG8_MMA(1, 0, At, B0); PG8_BAR; PG8_SCHED;
	s_add_u32 s48, s20, 0x40000
	s_addc_u32 s49, s21, 0
	s_add_i32 s33, s47, s30
	v_lshl_add_u64 v[142:143], s[48:49], 0, v[134:135]
	s_mov_b32 m0, s33
	s_nop 0
	global_load_lds_dwordx4 v[142:143], off
	v_lshl_add_u64 v[142:143], s[48:49], 0, v[132:133]
	s_add_i32 m0, s33, 0x2000
	s_nop 0
	global_load_lds_dwordx4 v[142:143], off
	s_waitcnt vmcnt(6)
	s_barrier
	v_mfma_f32_16x16x32_bf16 v[58:61], v[216:219], v[158:161], v[58:61]
	v_mfma_f32_16x16x32_bf16 v[50:53], v[224:227], v[158:161], v[50:53]
	v_mfma_f32_16x16x32_bf16 v[42:45], v[216:219], v[166:169], v[42:45]
	v_mfma_f32_16x16x32_bf16 v[34:37], v[224:227], v[166:169], v[34:37]
	v_mfma_f32_16x16x32_bf16 v[26:29], v[216:219], v[200:203], v[26:29]
	v_mfma_f32_16x16x32_bf16 v[18:21], v[224:227], v[200:203], v[18:21]
	v_mfma_f32_16x16x32_bf16 v[10:13], v[216:219], v[208:211], v[10:13]
	v_mfma_f32_16x16x32_bf16 v[2:5], v[224:227], v[208:211], v[2:5]
	v_mfma_f32_16x16x32_bf16 v[58:61], v[220:223], v[162:165], v[58:61]
	v_mfma_f32_16x16x32_bf16 v[50:53], v[228:231], v[162:165], v[50:53]
	v_mfma_f32_16x16x32_bf16 v[42:45], v[220:223], v[170:173], v[42:45]
	v_mfma_f32_16x16x32_bf16 v[34:37], v[228:231], v[170:173], v[34:37]
	v_mfma_f32_16x16x32_bf16 v[26:29], v[220:223], v[204:207], v[26:29]
	v_mfma_f32_16x16x32_bf16 v[18:21], v[228:231], v[204:207], v[18:21]
	v_mfma_f32_16x16x32_bf16 v[10:13], v[220:223], v[212:215], v[10:13]
	v_mfma_f32_16x16x32_bf16 v[2:5], v[228:231], v[212:215], v[2:5]
	s_barrier
	s_add_i32 s33, 0, 0x18000
	v_add_u32_e32 v154, s33, v131
	ds_read_b128 v[142:145], v154
	ds_read_b128 v[146:149], v154 offset:1024
	ds_read_b128 v[150:153], v154 offset:2048
	ds_read_b128 v[154:157], v154 offset:3072
	s_add_u32 s22, s22, 0x40000
	s_addc_u32 s23, s23, 0
	s_mov_b32 m0, s36
	v_lshl_add_u64 v[216:217], s[22:23], 0, v[134:135]
	ds_read_b128 v[158:161], v141 offset:32768
	ds_read_b128 v[162:165], v141 offset:33792
	ds_read_b128 v[166:169], v141 offset:34816
	ds_read_b128 v[170:173], v141 offset:35840
	ds_read_b128 v[200:203], v141 offset:36864
	ds_read_b128 v[204:207], v141 offset:37888
	ds_read_b128 v[208:211], v141 offset:38912
	ds_read_b128 v[212:215], v141 offset:39936
	global_load_lds_dwordx4 v[216:217], off
	v_lshl_add_u64 v[216:217], s[22:23], 0, v[132:133]
	s_mov_b32 m0, s37
	s_nop 0
	global_load_lds_dwordx4 v[216:217], off
	s_waitcnt lgkmcnt(8)
	s_barrier
	s_waitcnt lgkmcnt(0)
	v_mfma_f32_16x16x32_bf16 v[126:129], v[142:145], v[158:161], v[126:129]
	v_mfma_f32_16x16x32_bf16 v[118:121], v[150:153], v[158:161], v[118:121]
	v_mfma_f32_16x16x32_bf16 v[110:113], v[142:145], v[166:169], v[110:113]
	v_mfma_f32_16x16x32_bf16 v[102:105], v[150:153], v[166:169], v[102:105]
	v_mfma_f32_16x16x32_bf16 v[94:97], v[142:145], v[200:203], v[94:97]
	v_mfma_f32_16x16x32_bf16 v[86:89], v[150:153], v[200:203], v[86:89]
	v_mfma_f32_16x16x32_bf16 v[78:81], v[142:145], v[208:211], v[78:81]
	v_mfma_f32_16x16x32_bf16 v[70:73], v[150:153], v[208:211], v[70:73]
	v_mfma_f32_16x16x32_bf16 v[126:129], v[146:149], v[162:165], v[126:129]
	v_mfma_f32_16x16x32_bf16 v[118:121], v[154:157], v[162:165], v[118:121]
	v_mfma_f32_16x16x32_bf16 v[110:113], v[146:149], v[170:173], v[110:113]
	v_mfma_f32_16x16x32_bf16 v[102:105], v[154:157], v[170:173], v[102:105]
	v_mfma_f32_16x16x32_bf16 v[94:97], v[146:149], v[204:207], v[94:97]
	v_mfma_f32_16x16x32_bf16 v[86:89], v[154:157], v[204:207], v[86:89]
	v_mfma_f32_16x16x32_bf16 v[78:81], v[146:149], v[212:215], v[78:81]
	v_mfma_f32_16x16x32_bf16 v[70:73], v[154:157], v[212:215], v[70:73]
	s_barrier
	s_add_i32 s22, 0, 0x1c000
	s_add_i32 s23, s33, s30
	v_add_u32_e32 v228, s22, v131
	v_lshl_add_u64 v[174:175], v[174:175], 0, s[86:87]
	s_mov_b32 m0, s23
	ds_read_b128 v[216:219], v228
	ds_read_b128 v[220:223], v228 offset:1024
	ds_read_b128 v[224:227], v228 offset:2048
	ds_read_b128 v[228:231], v228 offset:3072
	global_load_lds_dwordx4 v[174:175], off
	v_lshl_add_u64 v[174:175], v[182:183], 0, s[86:87]
	s_add_i32 m0, s23, 0x2000
	s_nop 0
	global_load_lds_dwordx4 v[174:175], off
	s_barrier
	s_waitcnt lgkmcnt(0)
	v_mfma_f32_16x16x32_bf16 v[122:125], v[216:219], v[158:161], v[122:125]
	v_mfma_f32_16x16x32_bf16 v[114:117], v[224:227], v[158:161], v[114:117]
	v_mfma_f32_16x16x32_bf16 v[106:109], v[216:219], v[166:169], v[106:109]
	v_mfma_f32_16x16x32_bf16 v[98:101], v[224:227], v[166:169], v[98:101]
	v_mfma_f32_16x16x32_bf16 v[90:93], v[216:219], v[200:203], v[90:93]
	v_mfma_f32_16x16x32_bf16 v[82:85], v[224:227], v[200:203], v[82:85]
	v_mfma_f32_16x16x32_bf16 v[74:77], v[216:219], v[208:211], v[74:77]
	v_mfma_f32_16x16x32_bf16 v[66:69], v[224:227], v[208:211], v[66:69]
	v_mfma_f32_16x16x32_bf16 v[122:125], v[220:223], v[162:165], v[122:125]
	v_mfma_f32_16x16x32_bf16 v[114:117], v[228:231], v[162:165], v[114:117]
	v_mfma_f32_16x16x32_bf16 v[106:109], v[220:223], v[170:173], v[106:109]
	v_mfma_f32_16x16x32_bf16 v[98:101], v[228:231], v[170:173], v[98:101]
	v_mfma_f32_16x16x32_bf16 v[90:93], v[220:223], v[204:207], v[90:93]
	v_mfma_f32_16x16x32_bf16 v[82:85], v[228:231], v[204:207], v[82:85]
	v_mfma_f32_16x16x32_bf16 v[74:77], v[220:223], v[212:215], v[74:77]
	v_mfma_f32_16x16x32_bf16 v[66:69], v[228:231], v[212:215], v[66:69]
	s_barrier
	s_mov_b32 m0, s38
	v_lshl_add_u64 v[174:175], v[184:185], 0, s[86:87]
	ds_read_b128 v[158:161], v141 offset:49152
	ds_read_b128 v[162:165], v141 offset:50176
	ds_read_b128 v[166:169], v141 offset:51200
	ds_read_b128 v[170:173], v141 offset:52224
	ds_read_b128 v[200:203], v141 offset:53248
	ds_read_b128 v[204:207], v141 offset:54272
	ds_read_b128 v[208:211], v141 offset:55296
	ds_read_b128 v[212:215], v141 offset:56320
	global_load_lds_dwordx4 v[174:175], off
	v_lshl_add_u64 v[174:175], v[232:233], 0, s[86:87]
	s_mov_b32 m0, s39
	s_nop 0
	global_load_lds_dwordx4 v[174:175], off
	s_barrier
; __device__ __forceinline__ float silu_f(float x) { return x * sigm(x); }
; #define PG8_STAGE(bufoff, gbase, voff) do { _Pragma("unroll") for (int _i = 0; _i < 2; ++_i) \
;     __builtin_amdgcn_global_load_lds((const unsigned*)((const char*)(gbase) + (voff)[_i]), (PG8_LAS unsigned*)(lds + (bufoff) + ldsw + _i * 8192), 16, 0, 0); } while (0)
; #define PG8_MMA(ai, bj, At, Bt) do { __builtin_amdgcn_s_setprio(1); _Pragma("unroll") for (int m = 0; m < 4; ++m) _Pragma("unroll") for (int n = 0; n < 2; ++n) _Pragma("unroll") for (int k = 0; k < 2; ++k) \
;     acc[ai][bj][m][n] = __builtin_amdgcn_mfma_f32_16x16x32_bf16(Bt[n][k], At[m][k], acc[ai][bj][m][n], 0, 0, 0); __builtin_amdgcn_s_setprio(0); } while (0)
; #define PG8_WAIT_V(n) asm volatile("s_waitcnt vmcnt(" #n ")" ::: "memory")
; #define PG8_WAIT_L(n) asm volatile("s_waitcnt lgkmcnt(" #n ")" ::: "memory")
; #define PG8_BAR __builtin_amdgcn_s_barrier()
; #define PG8_SCHED __builtin_amdgcn_sched_barrier(0)
; template <class Epi, class Sched>
; __device__ __forceinline__ void gemm_phase(PG8_LAS unsigned char* lds, const int lda, const int ldb, const Sched& S, const Epi& E) {
;     ...
;       PG8_BAR; PG8_WAIT_L(0); PG8_MMA(1, 0, At, B0); PG8_BAR; PG8_SCHED;
;       PG8_STAGE(PG8_SB(1, 1), b3 + hstepB, voffB);
;       PG8_WAIT_V(6); PG8_BAR; PG8_MMA(1, 1, At, B1); PG8_BAR;
;   __device__ __forceinline__ void operator()(const f32x4 (&acc)[2][2][4][2], const Unit& u, int wr, int wc, int fr, int fq) const {
; #pragma unroll
;     for (int ai = 0; ai < 2; ++ai)
; #pragma unroll
;       for (int m = 0; m < 4; ++m) {
;         const int r = u.pm * 256 + ai * 128 + wr * 64 + m * 16 + fr;
; #pragma unroll
;         for (int n = 0; n < 2; ++n) {
;           const f32x4 g = acc[ai][0][m][n], up = acc[ai][1][m][n];
;           const int c = u.pn * 128 + wc * 32 + n * 16 + 4 * fq;
;           uint2 w;
;           w.x = pack2(silu_f(g[0]) * up[0], silu_f(g[1]) * up[1]);
;           w.y = pack2(silu_f(g[2]) * up[2], silu_f(g[3]) * up[3]);
;           *reinterpret_cast<uint2*>(HID + (size_t)r * DFF + c) = w;
;         }
;       }
;   }
	s_waitcnt lgkmcnt(0)
	v_mfma_f32_16x16x32_bf16 v[62:65], v[142:145], v[158:161], v[62:65]
	v_mfma_f32_16x16x32_bf16 v[54:57], v[150:153], v[158:161], v[54:57]
	v_mfma_f32_16x16x32_bf16 v[46:49], v[142:145], v[166:169], v[46:49]
	v_mfma_f32_16x16x32_bf16 v[38:41], v[150:153], v[166:169], v[38:41]
	v_mfma_f32_16x16x32_bf16 v[30:33], v[142:145], v[200:203], v[30:33]
	v_mfma_f32_16x16x32_bf16 v[22:25], v[150:153], v[200:203], v[22:25]
	v_mfma_f32_16x16x32_bf16 v[14:17], v[142:145], v[208:211], v[14:17]
	v_mfma_f32_16x16x32_bf16 v[6:9], v[150:153], v[208:211], v[6:9]
	v_mfma_f32_16x16x32_bf16 v[62:65], v[146:149], v[162:165], v[62:65]
	v_mfma_f32_16x16x32_bf16 v[54:57], v[154:157], v[162:165], v[54:57]
	v_mfma_f32_16x16x32_bf16 v[46:49], v[146:149], v[170:173], v[46:49]
	v_mfma_f32_16x16x32_bf16 v[38:41], v[154:157], v[170:173], v[38:41]
	v_mfma_f32_16x16x32_bf16 v[30:33], v[146:149], v[204:207], v[30:33]
	v_mfma_f32_16x16x32_bf16 v[22:25], v[154:157], v[204:207], v[22:25]
	v_mfma_f32_16x16x32_bf16 v[14:17], v[146:149], v[212:215], v[14:17]
	v_mfma_f32_16x16x32_bf16 v[6:9], v[154:157], v[212:215], v[6:9]
	s_barrier
	s_add_u32 s20, s20, 0x40080
	s_addc_u32 s21, s21, 0
	s_add_i32 s22, s22, s30
	v_lshl_add_u64 v[142:143], s[20:21], 0, v[134:135]
	s_mov_b32 m0, s22
	s_nop 0
	global_load_lds_dwordx4 v[142:143], off
	v_lshl_add_u64 v[142:143], s[20:21], 0, v[132:133]
	s_add_i32 m0, s22, 0x2000
	s_nop 0
	global_load_lds_dwordx4 v[142:143], off
	s_waitcnt vmcnt(6)
	s_barrier
	v_mfma_f32_16x16x32_bf16 v[58:61], v[216:219], v[158:161], v[58:61]
	v_mfma_f32_16x16x32_bf16 v[50:53], v[224:227], v[158:161], v[50:53]
	v_mfma_f32_16x16x32_bf16 v[42:45], v[216:219], v[166:169], v[42:45]
	v_mfma_f32_16x16x32_bf16 v[34:37], v[224:227], v[166:169], v[34:37]
	v_mfma_f32_16x16x32_bf16 v[26:29], v[216:219], v[200:203], v[26:29]
	v_mfma_f32_16x16x32_bf16 v[18:21], v[224:227], v[200:203], v[18:21]
	v_mfma_f32_16x16x32_bf16 v[10:13], v[216:219], v[208:211], v[10:13]
	v_mfma_f32_16x16x32_bf16 v[2:5], v[224:227], v[208:211], v[2:5]
	v_mfma_f32_16x16x32_bf16 v[58:61], v[220:223], v[162:165], v[58:61]
	v_mfma_f32_16x16x32_bf16 v[50:53], v[228:231], v[162:165], v[50:53]
	v_mfma_f32_16x16x32_bf16 v[42:45], v[220:223], v[170:173], v[42:45]
	v_mfma_f32_16x16x32_bf16 v[34:37], v[228:231], v[170:173], v[34:37]
	v_mfma_f32_16x16x32_bf16 v[26:29], v[220:223], v[204:207], v[26:29]
	v_mfma_f32_16x16x32_bf16 v[18:21], v[228:231], v[204:207], v[18:21]
	v_mfma_f32_16x16x32_bf16 v[10:13], v[220:223], v[212:215], v[10:13]
	v_mfma_f32_16x16x32_bf16 v[2:5], v[228:231], v[212:215], v[2:5]
	s_add_i32 s46, s46, 2
	s_add_u32 s18, s18, 0x100
	s_addc_u32 s19, s19, 0
	s_add_u32 s44, s44, 0x100
	s_addc_u32 s45, s45, 0
	s_cmp_gt_u32 s46, 13
	s_barrier
	s_cbranch_scc0 .LBB0_1604
	v_lshl_or_b32 v144, s41, 7, v140
	v_lshl_add_u32 v142, s16, 8, v1
	v_ashrrev_i32_e32 v145, 31, v144
	s_and_b64 vcc, exec, s[6:7]
	s_mov_b32 s41, s0
	s_mov_b32 s16, s10
	s_mov_b64 s[20:21], s[14:15]
	v_lshlrev_b64 v[146:147], 1, v[144:145]
	v_bfe_u32 v143, v176, 4, 1
	v_mul_u32_u24_e32 v143, 24, v143
	v_mov_b32_e32 v149, 0
	v_mov_b32_e32 v148, v143
	v_lshl_add_u64 v[146:147], v[146:147], 0, v[148:149]
	v_mov_b64_e32 v[148:149], s[84:85]
	v_mul_f32_e32 v150, 0xbfb8aa3b, v126
	v_mul_f32_e32 v151, 0xbfb8aa3b, v127
	v_mul_f32_e32 v152, 0xbfb8aa3b, v128
	v_mul_f32_e32 v153, 0xbfb8aa3b, v129
	v_mul_f32_e32 v154, 0xbfb8aa3b, v118
	v_mul_f32_e32 v155, 0xbfb8aa3b, v119
	v_mul_f32_e32 v156, 0xbfb8aa3b, v120
	v_mul_f32_e32 v157, 0xbfb8aa3b, v121
	v_exp_f32_e32 v150, v150
	v_exp_f32_e32 v151, v151
	v_exp_f32_e32 v152, v152
	v_exp_f32_e32 v153, v153
	v_exp_f32_e32 v154, v154
	v_exp_f32_e32 v155, v155
	v_exp_f32_e32 v156, v156
	v_exp_f32_e32 v157, v157
	v_add_f32_e32 v150, 1.0, v150
	v_add_f32_e32 v151, 1.0, v151
	v_add_f32_e32 v152, 1.0, v152
	v_add_f32_e32 v153, 1.0, v153
	v_add_f32_e32 v154, 1.0, v154
	v_add_f32_e32 v155, 1.0, v155
	v_add_f32_e32 v156, 1.0, v156
	v_add_f32_e32 v157, 1.0, v157
	v_rcp_f32_e32 v158, v150
	v_rcp_f32_e32 v159, v151
	v_rcp_f32_e32 v160, v152
	v_rcp_f32_e32 v161, v153
	v_rcp_f32_e32 v162, v154
	v_rcp_f32_e32 v163, v155
	v_rcp_f32_e32 v164, v156
	v_rcp_f32_e32 v165, v157
	v_mov_b32_e32 v212, v142
	v_mad_i64_i32 v[208:209], s[18:19], v212, s50, v[148:149]
	v_lshl_add_u64 v[208:209], v[208:209], 0, v[146:147]
	v_pk_mul_f32 v[166:167], v[126:127], v[158:159]
	v_pk_mul_f32 v[168:169], v[128:129], v[160:161]
	v_pk_mul_f32 v[170:171], v[118:119], v[162:163]
	v_pk_mul_f32 v[172:173], v[120:121], v[164:165]
	v_pk_mul_f32 v[166:167], v[166:167], v[122:123]
	v_pk_mul_f32 v[168:169], v[168:169], v[124:125]
	v_pk_mul_f32 v[170:171], v[170:171], v[114:115]
	v_pk_mul_f32 v[172:173], v[172:173], v[116:117]
	v_cvt_pk_bf16_f32 v200, v166, v167
	v_cvt_pk_bf16_f32 v201, v168, v169
	v_cvt_pk_bf16_f32 v202, v170, v171
	v_cvt_pk_bf16_f32 v203, v172, v173
	s_nop 1
	v_permlane16_swap_b32_e32 v200, v202
	v_permlane16_swap_b32_e32 v201, v203
	global_store_dwordx4 v[208:209], v[200:203], off
	v_mul_f32_e32 v150, 0xbfb8aa3b, v110
	v_mul_f32_e32 v151, 0xbfb8aa3b, v111
	v_mul_f32_e32 v152, 0xbfb8aa3b, v112
	v_mul_f32_e32 v153, 0xbfb8aa3b, v113
	v_mul_f32_e32 v154, 0xbfb8aa3b, v102
	v_mul_f32_e32 v155, 0xbfb8aa3b, v103
	v_mul_f32_e32 v156, 0xbfb8aa3b, v104
	v_mul_f32_e32 v157, 0xbfb8aa3b, v105
	v_exp_f32_e32 v150, v150
	v_exp_f32_e32 v151, v151
	v_exp_f32_e32 v152, v152
	v_exp_f32_e32 v153, v153
	v_exp_f32_e32 v154, v154
	v_exp_f32_e32 v155, v155
	v_exp_f32_e32 v156, v156
	v_exp_f32_e32 v157, v157
	v_add_f32_e32 v150, 1.0, v150
	v_add_f32_e32 v151, 1.0, v151
	v_add_f32_e32 v152, 1.0, v152
	v_add_f32_e32 v153, 1.0, v153
	v_add_f32_e32 v154, 1.0, v154
; __device__ __forceinline__ float silu_f(float x) { return x * sigm(x); }
;   __device__ __forceinline__ void operator()(const f32x4 (&acc)[2][2][4][2], const Unit& u, int wr, int wc, int fr, int fq) const {
; #pragma unroll
;     for (int ai = 0; ai < 2; ++ai)
; #pragma unroll
;       for (int m = 0; m < 4; ++m) {
;         const int r = u.pm * 256 + ai * 128 + wr * 64 + m * 16 + fr;
; #pragma unroll
;         for (int n = 0; n < 2; ++n) {
;           const f32x4 g = acc[ai][0][m][n], up = acc[ai][1][m][n];
;           const int c = u.pn * 128 + wc * 32 + n * 16 + 4 * fq;
;           uint2 w;
;           w.x = pack2(silu_f(g[0]) * up[0], silu_f(g[1]) * up[1]);
;           w.y = pack2(silu_f(g[2]) * up[2], silu_f(g[3]) * up[3]);
;           *reinterpret_cast<uint2*>(HID + (size_t)r * DFF + c) = w;
;         }
;       }
;   }
	v_add_f32_e32 v155, 1.0, v155
	v_add_f32_e32 v156, 1.0, v156
	v_add_f32_e32 v157, 1.0, v157
	v_rcp_f32_e32 v158, v150
	v_rcp_f32_e32 v159, v151
	v_rcp_f32_e32 v160, v152
	v_rcp_f32_e32 v161, v153
	v_rcp_f32_e32 v162, v154
	v_rcp_f32_e32 v163, v155
	v_rcp_f32_e32 v164, v156
	v_rcp_f32_e32 v165, v157
	v_add_u32_e32 v212, 0x10, v142
	v_mad_i64_i32 v[210:211], s[18:19], v212, s50, v[148:149]
	v_lshl_add_u64 v[210:211], v[210:211], 0, v[146:147]
	v_pk_mul_f32 v[166:167], v[110:111], v[158:159]
	v_pk_mul_f32 v[168:169], v[112:113], v[160:161]
	v_pk_mul_f32 v[170:171], v[102:103], v[162:163]
	v_pk_mul_f32 v[172:173], v[104:105], v[164:165]
	v_pk_mul_f32 v[166:167], v[166:167], v[106:107]
	v_pk_mul_f32 v[168:169], v[168:169], v[108:109]
	v_pk_mul_f32 v[170:171], v[170:171], v[98:99]
	v_pk_mul_f32 v[172:173], v[172:173], v[100:101]
	v_cvt_pk_bf16_f32 v204, v166, v167
	v_cvt_pk_bf16_f32 v205, v168, v169
	v_cvt_pk_bf16_f32 v206, v170, v171
	v_cvt_pk_bf16_f32 v207, v172, v173
	s_nop 1
	v_permlane16_swap_b32_e32 v204, v206
	v_permlane16_swap_b32_e32 v205, v207
	global_store_dwordx4 v[210:211], v[204:207], off
	v_mul_f32_e32 v150, 0xbfb8aa3b, v94
	v_mul_f32_e32 v151, 0xbfb8aa3b, v95
	v_mul_f32_e32 v152, 0xbfb8aa3b, v96
	v_mul_f32_e32 v153, 0xbfb8aa3b, v97
	v_mul_f32_e32 v154, 0xbfb8aa3b, v86
	v_mul_f32_e32 v155, 0xbfb8aa3b, v87
	v_mul_f32_e32 v156, 0xbfb8aa3b, v88
	v_mul_f32_e32 v157, 0xbfb8aa3b, v89
	v_exp_f32_e32 v150, v150
	v_exp_f32_e32 v151, v151
	v_exp_f32_e32 v152, v152
	v_exp_f32_e32 v153, v153
	v_exp_f32_e32 v154, v154
	v_exp_f32_e32 v155, v155
	v_exp_f32_e32 v156, v156
	v_exp_f32_e32 v157, v157
	v_add_f32_e32 v150, 1.0, v150
	v_add_f32_e32 v151, 1.0, v151
	v_add_f32_e32 v152, 1.0, v152
	v_add_f32_e32 v153, 1.0, v153
	v_add_f32_e32 v154, 1.0, v154
	v_add_f32_e32 v155, 1.0, v155
	v_add_f32_e32 v156, 1.0, v156
	v_add_f32_e32 v157, 1.0, v157
	v_rcp_f32_e32 v158, v150
	v_rcp_f32_e32 v159, v151
	v_rcp_f32_e32 v160, v152
	v_rcp_f32_e32 v161, v153
	v_rcp_f32_e32 v162, v154
	v_rcp_f32_e32 v163, v155
	v_rcp_f32_e32 v164, v156
	v_rcp_f32_e32 v165, v157
	v_add_u32_e32 v212, 0x20, v142
	v_mad_i64_i32 v[208:209], s[18:19], v212, s50, v[148:149]
	v_lshl_add_u64 v[208:209], v[208:209], 0, v[146:147]
	v_pk_mul_f32 v[166:167], v[94:95], v[158:159]
	v_pk_mul_f32 v[168:169], v[96:97], v[160:161]
	v_pk_mul_f32 v[170:171], v[86:87], v[162:163]
	v_pk_mul_f32 v[172:173], v[88:89], v[164:165]
	v_pk_mul_f32 v[166:167], v[166:167], v[90:91]
	v_pk_mul_f32 v[168:169], v[168:169], v[92:93]
	v_pk_mul_f32 v[170:171], v[170:171], v[82:83]
	v_pk_mul_f32 v[172:173], v[172:173], v[84:85]
	v_cvt_pk_bf16_f32 v200, v166, v167
	v_cvt_pk_bf16_f32 v201, v168, v169
	v_cvt_pk_bf16_f32 v202, v170, v171
	v_cvt_pk_bf16_f32 v203, v172, v173
	s_nop 1
	v_permlane16_swap_b32_e32 v200, v202
	v_permlane16_swap_b32_e32 v201, v203
	global_store_dwordx4 v[208:209], v[200:203], off
	v_mul_f32_e32 v150, 0xbfb8aa3b, v78
	v_mul_f32_e32 v151, 0xbfb8aa3b, v79
	v_mul_f32_e32 v152, 0xbfb8aa3b, v80
	v_mul_f32_e32 v153, 0xbfb8aa3b, v81
	v_mul_f32_e32 v154, 0xbfb8aa3b, v70
	v_mul_f32_e32 v155, 0xbfb8aa3b, v71
	v_mul_f32_e32 v156, 0xbfb8aa3b, v72
	v_mul_f32_e32 v157, 0xbfb8aa3b, v73
	v_exp_f32_e32 v150, v150
	v_exp_f32_e32 v151, v151
	v_exp_f32_e32 v152, v152
	v_exp_f32_e32 v153, v153
	v_exp_f32_e32 v154, v154
	v_exp_f32_e32 v155, v155
	v_exp_f32_e32 v156, v156
	v_exp_f32_e32 v157, v157
	v_add_f32_e32 v150, 1.0, v150
	v_add_f32_e32 v151, 1.0, v151
	v_add_f32_e32 v152, 1.0, v152
	v_add_f32_e32 v153, 1.0, v153
	v_add_f32_e32 v154, 1.0, v154
	v_add_f32_e32 v155, 1.0, v155
	v_add_f32_e32 v156, 1.0, v156
	v_add_f32_e32 v157, 1.0, v157
	v_rcp_f32_e32 v158, v150
	v_rcp_f32_e32 v159, v151
	v_rcp_f32_e32 v160, v152
	v_rcp_f32_e32 v161, v153
	v_rcp_f32_e32 v162, v154
	v_rcp_f32_e32 v163, v155
	v_rcp_f32_e32 v164, v156
	v_rcp_f32_e32 v165, v157
	v_add_u32_e32 v212, 0x30, v142
	v_mad_i64_i32 v[210:211], s[18:19], v212, s50, v[148:149]
	v_lshl_add_u64 v[210:211], v[210:211], 0, v[146:147]
	v_pk_mul_f32 v[166:167], v[78:79], v[158:159]
	v_pk_mul_f32 v[168:169], v[80:81], v[160:161]
	v_pk_mul_f32 v[170:171], v[70:71], v[162:163]
	v_pk_mul_f32 v[172:173], v[72:73], v[164:165]
	v_pk_mul_f32 v[166:167], v[166:167], v[74:75]
	v_pk_mul_f32 v[168:169], v[168:169], v[76:77]
	v_pk_mul_f32 v[170:171], v[170:171], v[66:67]
	v_pk_mul_f32 v[172:173], v[172:173], v[68:69]
	v_cvt_pk_bf16_f32 v204, v166, v167
	v_cvt_pk_bf16_f32 v205, v168, v169
	v_cvt_pk_bf16_f32 v206, v170, v171
	v_cvt_pk_bf16_f32 v207, v172, v173
	s_nop 1
	v_permlane16_swap_b32_e32 v204, v206
	v_permlane16_swap_b32_e32 v205, v207
	global_store_dwordx4 v[210:211], v[204:207], off
	v_mul_f32_e32 v150, 0xbfb8aa3b, v62
	v_mul_f32_e32 v151, 0xbfb8aa3b, v63
	v_mul_f32_e32 v152, 0xbfb8aa3b, v64
	v_mul_f32_e32 v153, 0xbfb8aa3b, v65
	v_mul_f32_e32 v154, 0xbfb8aa3b, v54
	v_mul_f32_e32 v155, 0xbfb8aa3b, v55
	v_mul_f32_e32 v156, 0xbfb8aa3b, v56
	v_mul_f32_e32 v157, 0xbfb8aa3b, v57
	v_exp_f32_e32 v150, v150
	v_exp_f32_e32 v151, v151
	v_exp_f32_e32 v152, v152
	v_exp_f32_e32 v153, v153
	v_exp_f32_e32 v154, v154
	v_exp_f32_e32 v155, v155
	v_exp_f32_e32 v156, v156
	v_exp_f32_e32 v157, v157
	v_add_f32_e32 v150, 1.0, v150
	v_add_f32_e32 v151, 1.0, v151
	v_add_f32_e32 v152, 1.0, v152
	v_add_f32_e32 v153, 1.0, v153
	v_add_f32_e32 v154, 1.0, v154
	v_add_f32_e32 v155, 1.0, v155
	v_add_f32_e32 v156, 1.0, v156
	v_add_f32_e32 v157, 1.0, v157
	v_rcp_f32_e32 v158, v150
	v_rcp_f32_e32 v159, v151
	v_rcp_f32_e32 v160, v152
	v_rcp_f32_e32 v161, v153
	v_rcp_f32_e32 v162, v154
	v_rcp_f32_e32 v163, v155
	v_rcp_f32_e32 v164, v156
	v_rcp_f32_e32 v165, v157
	v_add_u32_e32 v212, 0x80, v142
; __device__ __forceinline__ float silu_f(float x) { return x * sigm(x); }
; #define PG8_WAIT_V(n) asm volatile("s_waitcnt vmcnt(" #n ")" ::: "memory")
; #define PG8_BAR __builtin_amdgcn_s_barrier()
;   __device__ __forceinline__ int kt(const Unit& u) const { return ((u.pn & 7) < 4) ? 4 : 16; }
; template <class Epi, class Sched>
; __device__ __forceinline__ void gemm_phase(PG8_LAS unsigned char* lds, const int lda, const int ldb, const Sched& S, const Epi& E) {
;     ...
;     cur = nxt; cA = nA; cB = nB; ++ui;
;     nt = S.kt(cur);
;   }
;   PG8_WAIT_V(0);
;   if (wr == 0) PG8_BAR;
;   PG8_BAR;
;   __device__ __forceinline__ void operator()(const f32x4 (&acc)[2][2][4][2], const Unit& u, int wr, int wc, int fr, int fq) const {
; #pragma unroll
;     for (int ai = 0; ai < 2; ++ai)
; #pragma unroll
;       for (int m = 0; m < 4; ++m) {
;         const int r = u.pm * 256 + ai * 128 + wr * 64 + m * 16 + fr;
; #pragma unroll
;         for (int n = 0; n < 2; ++n) {
;           const f32x4 g = acc[ai][0][m][n], up = acc[ai][1][m][n];
;           const int c = u.pn * 128 + wc * 32 + n * 16 + 4 * fq;
;           uint2 w;
;           w.x = pack2(silu_f(g[0]) * up[0], silu_f(g[1]) * up[1]);
;           w.y = pack2(silu_f(g[2]) * up[2], silu_f(g[3]) * up[3]);
;           *reinterpret_cast<uint2*>(HID + (size_t)r * DFF + c) = w;
;         }
;       }
;   }
	v_mad_i64_i32 v[208:209], s[18:19], v212, s50, v[148:149]
	v_lshl_add_u64 v[208:209], v[208:209], 0, v[146:147]
	v_pk_mul_f32 v[166:167], v[62:63], v[158:159]
	v_pk_mul_f32 v[168:169], v[64:65], v[160:161]
	v_pk_mul_f32 v[170:171], v[54:55], v[162:163]
	v_pk_mul_f32 v[172:173], v[56:57], v[164:165]
	v_pk_mul_f32 v[166:167], v[166:167], v[58:59]
	v_pk_mul_f32 v[168:169], v[168:169], v[60:61]
	v_pk_mul_f32 v[170:171], v[170:171], v[50:51]
	v_pk_mul_f32 v[172:173], v[172:173], v[52:53]
	v_cvt_pk_bf16_f32 v200, v166, v167
	v_cvt_pk_bf16_f32 v201, v168, v169
	v_cvt_pk_bf16_f32 v202, v170, v171
	v_cvt_pk_bf16_f32 v203, v172, v173
	s_nop 1
	v_permlane16_swap_b32_e32 v200, v202
	v_permlane16_swap_b32_e32 v201, v203
	global_store_dwordx4 v[208:209], v[200:203], off
	v_mul_f32_e32 v150, 0xbfb8aa3b, v46
	v_mul_f32_e32 v151, 0xbfb8aa3b, v47
	v_mul_f32_e32 v152, 0xbfb8aa3b, v48
	v_mul_f32_e32 v153, 0xbfb8aa3b, v49
	v_mul_f32_e32 v154, 0xbfb8aa3b, v38
	v_mul_f32_e32 v155, 0xbfb8aa3b, v39
	v_mul_f32_e32 v156, 0xbfb8aa3b, v40
	v_mul_f32_e32 v157, 0xbfb8aa3b, v41
	v_exp_f32_e32 v150, v150
	v_exp_f32_e32 v151, v151
	v_exp_f32_e32 v152, v152
	v_exp_f32_e32 v153, v153
	v_exp_f32_e32 v154, v154
	v_exp_f32_e32 v155, v155
	v_exp_f32_e32 v156, v156
	v_exp_f32_e32 v157, v157
	v_add_f32_e32 v150, 1.0, v150
	v_add_f32_e32 v151, 1.0, v151
	v_add_f32_e32 v152, 1.0, v152
	v_add_f32_e32 v153, 1.0, v153
	v_add_f32_e32 v154, 1.0, v154
	v_add_f32_e32 v155, 1.0, v155
	v_add_f32_e32 v156, 1.0, v156
	v_add_f32_e32 v157, 1.0, v157
	v_rcp_f32_e32 v158, v150
	v_rcp_f32_e32 v159, v151
	v_rcp_f32_e32 v160, v152
	v_rcp_f32_e32 v161, v153
	v_rcp_f32_e32 v162, v154
	v_rcp_f32_e32 v163, v155
	v_rcp_f32_e32 v164, v156
	v_rcp_f32_e32 v165, v157
	v_add_u32_e32 v212, 0x90, v142
	v_mad_i64_i32 v[210:211], s[18:19], v212, s50, v[148:149]
	v_lshl_add_u64 v[210:211], v[210:211], 0, v[146:147]
	v_pk_mul_f32 v[166:167], v[46:47], v[158:159]
	v_pk_mul_f32 v[168:169], v[48:49], v[160:161]
	v_pk_mul_f32 v[170:171], v[38:39], v[162:163]
	v_pk_mul_f32 v[172:173], v[40:41], v[164:165]
	v_pk_mul_f32 v[166:167], v[166:167], v[42:43]
	v_pk_mul_f32 v[168:169], v[168:169], v[44:45]
	v_pk_mul_f32 v[170:171], v[170:171], v[34:35]
	v_pk_mul_f32 v[172:173], v[172:173], v[36:37]
	v_cvt_pk_bf16_f32 v204, v166, v167
	v_cvt_pk_bf16_f32 v205, v168, v169
	v_cvt_pk_bf16_f32 v206, v170, v171
	v_cvt_pk_bf16_f32 v207, v172, v173
	s_nop 1
	v_permlane16_swap_b32_e32 v204, v206
	v_permlane16_swap_b32_e32 v205, v207
	global_store_dwordx4 v[210:211], v[204:207], off
	v_mul_f32_e32 v150, 0xbfb8aa3b, v30
	v_mul_f32_e32 v151, 0xbfb8aa3b, v31
	v_mul_f32_e32 v152, 0xbfb8aa3b, v32
	v_mul_f32_e32 v153, 0xbfb8aa3b, v33
	v_mul_f32_e32 v154, 0xbfb8aa3b, v22
	v_mul_f32_e32 v155, 0xbfb8aa3b, v23
	v_mul_f32_e32 v156, 0xbfb8aa3b, v24
	v_mul_f32_e32 v157, 0xbfb8aa3b, v25
	v_exp_f32_e32 v150, v150
	v_exp_f32_e32 v151, v151
	v_exp_f32_e32 v152, v152
	v_exp_f32_e32 v153, v153
	v_exp_f32_e32 v154, v154
	v_exp_f32_e32 v155, v155
	v_exp_f32_e32 v156, v156
	v_exp_f32_e32 v157, v157
	v_add_f32_e32 v150, 1.0, v150
	v_add_f32_e32 v151, 1.0, v151
	v_add_f32_e32 v152, 1.0, v152
	v_add_f32_e32 v153, 1.0, v153
	v_add_f32_e32 v154, 1.0, v154
	v_add_f32_e32 v155, 1.0, v155
	v_add_f32_e32 v156, 1.0, v156
	v_add_f32_e32 v157, 1.0, v157
	v_rcp_f32_e32 v158, v150
	v_rcp_f32_e32 v159, v151
	v_rcp_f32_e32 v160, v152
	v_rcp_f32_e32 v161, v153
	v_rcp_f32_e32 v162, v154
	v_rcp_f32_e32 v163, v155
	v_rcp_f32_e32 v164, v156
	v_rcp_f32_e32 v165, v157
	v_add_u32_e32 v212, 0xa0, v142
	v_mad_i64_i32 v[208:209], s[18:19], v212, s50, v[148:149]
	v_lshl_add_u64 v[208:209], v[208:209], 0, v[146:147]
	v_pk_mul_f32 v[166:167], v[30:31], v[158:159]
	v_pk_mul_f32 v[168:169], v[32:33], v[160:161]
	v_pk_mul_f32 v[170:171], v[22:23], v[162:163]
	v_pk_mul_f32 v[172:173], v[24:25], v[164:165]
	v_pk_mul_f32 v[166:167], v[166:167], v[26:27]
	v_pk_mul_f32 v[168:169], v[168:169], v[28:29]
	v_pk_mul_f32 v[170:171], v[170:171], v[18:19]
	v_pk_mul_f32 v[172:173], v[172:173], v[20:21]
	v_cvt_pk_bf16_f32 v200, v166, v167
	v_cvt_pk_bf16_f32 v201, v168, v169
	v_cvt_pk_bf16_f32 v202, v170, v171
	v_cvt_pk_bf16_f32 v203, v172, v173
	s_nop 1
	v_permlane16_swap_b32_e32 v200, v202
	v_permlane16_swap_b32_e32 v201, v203
	global_store_dwordx4 v[208:209], v[200:203], off
	v_mul_f32_e32 v150, 0xbfb8aa3b, v14
	v_mul_f32_e32 v151, 0xbfb8aa3b, v15
	v_mul_f32_e32 v152, 0xbfb8aa3b, v16
	v_mul_f32_e32 v153, 0xbfb8aa3b, v17
	v_mul_f32_e32 v154, 0xbfb8aa3b, v6
	v_mul_f32_e32 v155, 0xbfb8aa3b, v7
	v_mul_f32_e32 v156, 0xbfb8aa3b, v8
	v_mul_f32_e32 v157, 0xbfb8aa3b, v9
	v_exp_f32_e32 v150, v150
	v_exp_f32_e32 v151, v151
	v_exp_f32_e32 v152, v152
	v_exp_f32_e32 v153, v153
	v_exp_f32_e32 v154, v154
	v_exp_f32_e32 v155, v155
	v_exp_f32_e32 v156, v156
	v_exp_f32_e32 v157, v157
	v_add_f32_e32 v150, 1.0, v150
	v_add_f32_e32 v151, 1.0, v151
	v_add_f32_e32 v152, 1.0, v152
	v_add_f32_e32 v153, 1.0, v153
	v_add_f32_e32 v154, 1.0, v154
	v_add_f32_e32 v155, 1.0, v155
	v_add_f32_e32 v156, 1.0, v156
	v_add_f32_e32 v157, 1.0, v157
	v_rcp_f32_e32 v158, v150
	v_rcp_f32_e32 v159, v151
	v_rcp_f32_e32 v160, v152
	v_rcp_f32_e32 v161, v153
	v_rcp_f32_e32 v162, v154
	v_rcp_f32_e32 v163, v155
	v_rcp_f32_e32 v164, v156
	v_rcp_f32_e32 v165, v157
	v_add_u32_e32 v212, 0xb0, v142
	v_mad_i64_i32 v[210:211], s[18:19], v212, s50, v[148:149]
	v_lshl_add_u64 v[210:211], v[210:211], 0, v[146:147]
	v_pk_mul_f32 v[166:167], v[14:15], v[158:159]
	v_pk_mul_f32 v[168:169], v[16:17], v[160:161]
	v_pk_mul_f32 v[170:171], v[6:7], v[162:163]
	v_pk_mul_f32 v[172:173], v[8:9], v[164:165]
	v_pk_mul_f32 v[166:167], v[166:167], v[10:11]
	v_pk_mul_f32 v[168:169], v[168:169], v[12:13]
	v_pk_mul_f32 v[170:171], v[170:171], v[2:3]
	v_pk_mul_f32 v[172:173], v[172:173], v[4:5]
	v_cvt_pk_bf16_f32 v204, v166, v167
	v_cvt_pk_bf16_f32 v205, v168, v169
	v_cvt_pk_bf16_f32 v206, v170, v171
	v_cvt_pk_bf16_f32 v207, v172, v173
	s_nop 1
	v_permlane16_swap_b32_e32 v204, v206
	v_permlane16_swap_b32_e32 v205, v207
	global_store_dwordx4 v[210:211], v[204:207], off
	s_mov_b64 s[18:19], s[12:13]
	s_cbranch_vccz .LBB0_1601
	s_waitcnt vmcnt(0)
	v_readlane_b32 s40, v253, 12
	s_cmpk_gt_u32 s9, 0xff
	v_readlane_b32 s41, v253, 13
	v_readlane_b32 s44, v253, 16
	v_readlane_b32 s45, v253, 17
	v_readlane_b32 s52, v253, 24
	v_readlane_b32 s53, v253, 25
	v_readlane_b32 s54, v253, 26
	v_readlane_b32 s55, v253, 27
	v_readlane_b32 s38, v255, 23
	v_readlane_b32 s42, v253, 14
	v_readlane_b32 s43, v253, 15
	v_readlane_b32 s46, v253, 18
	v_readlane_b32 s47, v253, 19
	v_readlane_b32 s48, v253, 20
	v_readlane_b32 s49, v253, 21
	v_readlane_b32 s50, v253, 22
	v_readlane_b32 s51, v253, 23
	v_readlane_b32 s39, v255, 24
	s_cbranch_scc1 .LBB0_1608
	s_barrier
